# removed the RG-LRU gate-to-scan workgroup barrier (producer and consumer are the same wave) on v19
# speedup vs baseline: 1.0044x; 1.0032x over previous
; #define LAS __attribute__((address_space(3)))
; __device__ __forceinline__ float fsigmoid(float x) { return __builtin_amdgcn_rcpf(1.0f + __builtin_amdgcn_exp2f(-1.4426950408889634f * x)); }
; __device__ __forceinline__ void rglru_unit(LAS unsigned char* lds, int unit, const bf16* PBp, bf16* MGp, float* SSQRp, const float* cw, const float* cbias, const float* wa, const float* ba, const float* wx, const float* bxp, const float* lam) {
;     ...
;         {
;             typedef float f32x4m __attribute__((ext_vector_type(4)));
;             const rg_bf16x8 a0 = *(const LAS rg_bf16x8*)(XRB + (wave * 16 + fr) * 72 + 8 * fq), a1 = *(const LAS rg_bf16x8*)(XRB + (wave * 16 + fr) * 72 + 32 + 8 * fq);
;             f32x4m d[4];
; #pragma unroll
;             for (int nb = 0; nb < 4; ++nb) { d[nb] = (f32x4m){0.f, 0.f, 0.f, 0.f};
;                 d[nb] = __builtin_amdgcn_mfma_f32_16x16x32_bf16(a0, wb[nb][0], d[nb], 0, 0, 0); d[nb] = __builtin_amdgcn_mfma_f32_16x16x32_bf16(a1, wb[nb][1], d[nb], 0, 0, 0); }
; #pragma unroll
;             for (int cb = 0; cb < 2; ++cb)
; #pragma unroll
;                 for (int e = 0; e < 4; ++e) {
;                     const int tok = wave * 16 + 4 * fq + e, cl = 16 * cb + fr;
;                     const float r = fsigmoid(d[cb][e] + gba[cb]), ig = fsigmoid(d[2 + cb][e] + gbx[cb]);
;                     const float a = __builtin_amdgcn_exp2f(r * gsp[cb]);
;                     const float om = fmaxf(1.0f - a * a, 0.0f);
;                     AL[tok * 32 + cl] = a; UL[tok * 32 + cl] = __builtin_amdgcn_sqrtf(om) * (ig * XRF[tok * 32 + cl]);
;                 }
;         }
;         __syncthreads();
;         float av[8], uv[8];
; #pragma unroll
;         for (int k = 0; k < 8; ++k) { av[k] = AL[(ss * 8 + k) * 32 + sc]; uv[k] = UL[(ss * 8 + k) * 32 + sc]; }
;         { float h = 0.f, p = 1.f;
; #pragma unroll
;           for (int k = 0; k < 8; ++k) { h = av[k] * h + uv[k]; p *= av[k]; }
;           PE[(ss * 32 + sc) * 2] = p; PE[(ss * 32 + sc) * 2 + 1] = h; }
.LBB0_452:
	s_waitcnt lgkmcnt(0)
	s_barrier
	ds_read_b128 v[72:75], v134
	ds_read_b128 v[76:79], v134 offset:64
	s_waitcnt lgkmcnt(1)
	v_mfma_f32_16x16x32_bf16 v[80:83], v[72:75], v[20:23], 0
	ds_read_b32 v1, v138 offset:18432
	ds_read_b32 v92, v138 offset:18816
	s_waitcnt lgkmcnt(2)
	v_mfma_f32_16x16x32_bf16 v[80:83], v[76:79], v[32:35], v[80:83]
	v_mfma_f32_16x16x32_bf16 v[84:87], v[72:75], v[52:55], 0
	v_mfma_f32_16x16x32_bf16 v[84:87], v[76:79], v[56:59], v[84:87]
	s_nop 5
	v_add_f32_e32 v2, v122, v80
	v_mul_f32_e32 v2, 0xbfb8aa3b, v2
	v_exp_f32_e32 v2, v2
	v_add_f32_e32 v80, v122, v81
	v_mul_f32_e32 v80, 0xbfb8aa3b, v80
	v_add_f32_e32 v3, v123, v84
	v_add_f32_e32 v2, 1.0, v2
	v_rcp_f32_e32 v2, v2
	v_mul_f32_e32 v3, 0xbfb8aa3b, v3
	v_mfma_f32_16x16x32_bf16 v[88:91], v[72:75], v[36:39], 0
	v_exp_f32_e32 v3, v3
	v_mul_f32_e32 v2, v128, v2
	v_exp_f32_e32 v84, v2
	v_mfma_f32_16x16x32_bf16 v[72:75], v[72:75], v[60:63], 0
	v_exp_f32_e32 v80, v80
	v_add_f32_e32 v3, 1.0, v3
	v_rcp_f32_e32 v3, v3
	v_mfma_f32_16x16x32_bf16 v[88:91], v[76:79], v[48:51], v[88:91]
	v_add_f32_e32 v2, 1.0, v80
	v_add_f32_e32 v81, v123, v85
	v_rcp_f32_e32 v2, v2
	v_mfma_f32_16x16x32_bf16 v[72:75], v[76:79], v[64:67], v[72:75]
	v_fma_f32 v76, -v84, v84, 1.0
	v_max_f32_e32 v76, 0, v76
	v_sqrt_f32_e32 v76, v76
	v_mul_f32_e32 v81, 0xbfb8aa3b, v81
	v_exp_f32_e32 v77, v81
	s_waitcnt lgkmcnt(1)
	v_mul_f32_e32 v1, v1, v3
	v_mul_f32_e32 v1, v1, v76
	v_mul_f32_e32 v2, v128, v2
	v_exp_f32_e32 v76, v2
	ds_write_b32 v138, v1 offset:51200
	v_add_u32_e32 v2, 0x4800, v138
	v_add_f32_e32 v78, v122, v82
	v_add_f32_e32 v1, 1.0, v77
	ds_read2_b32 v[2:3], v2 offset0:32 offset1:64
	v_mul_f32_e32 v78, 0xbfb8aa3b, v78
	v_rcp_f32_e32 v1, v1
	v_exp_f32_e32 v78, v78
	v_fma_f32 v77, -v76, v76, 1.0
	v_add_u32_e32 v79, 0x8800, v138
	s_waitcnt lgkmcnt(0)
	v_mul_f32_e32 v1, v1, v2
	v_add_f32_e32 v2, 1.0, v78
	v_rcp_f32_e32 v2, v2
	v_add_f32_e32 v78, v123, v86
	v_max_f32_e32 v77, 0, v77
	v_mul_f32_e32 v78, 0xbfb8aa3b, v78
	v_mul_f32_e32 v2, v128, v2
	v_exp_f32_e32 v2, v2
	v_sqrt_f32_e32 v77, v77
	v_exp_f32_e32 v78, v78
	v_add_f32_e32 v74, v125, v74
	ds_write2_b32 v79, v76, v2 offset0:32 offset1:64
	v_add_f32_e32 v76, v122, v83
	v_mul_f32_e32 v76, 0xbfb8aa3b, v76
	v_exp_f32_e32 v76, v76
	v_mul_f32_e32 v1, v1, v77
	v_add_f32_e32 v77, 1.0, v78
	v_rcp_f32_e32 v77, v77
	v_add_f32_e32 v76, 1.0, v76
	v_rcp_f32_e32 v76, v76
	v_fma_f32 v78, -v2, v2, 1.0
	v_max_f32_e32 v78, 0, v78
	v_mul_f32_e32 v3, v77, v3
	v_add_f32_e32 v77, v123, v87
	v_sqrt_f32_e32 v2, v78
	v_mul_f32_e32 v77, 0xbfb8aa3b, v77
	v_mul_f32_e32 v76, v128, v76
	v_exp_f32_e32 v77, v77
	v_exp_f32_e32 v76, v76
	v_mul_f32_e32 v2, v2, v3
	v_add_u32_e32 v3, 0xc800, v138
	ds_write2_b32 v3, v1, v2 offset0:32 offset1:64
	v_add_f32_e32 v1, 1.0, v77
	v_fma_f32 v2, -v76, v76, 1.0
	v_add_f32_e32 v3, v124, v88
	v_rcp_f32_e32 v1, v1
	v_max_f32_e32 v2, 0, v2
	v_mul_f32_e32 v3, 0xbfb8aa3b, v3
	v_sqrt_f32_e32 v2, v2
	v_exp_f32_e32 v3, v3
	v_mul_f32_e32 v1, v1, v92
	ds_write_b32 v138, v76 offset:35200
	v_mul_f32_e32 v1, v2, v1
	v_add_f32_e32 v2, 1.0, v3
	v_rcp_f32_e32 v2, v2
	v_add_f32_e32 v3, v125, v72
	v_mul_f32_e32 v3, 0xbfb8aa3b, v3
	v_exp_f32_e32 v3, v3
	v_mul_f32_e32 v2, v127, v2
	v_exp_f32_e32 v2, v2
	ds_write_b32 v138, v1 offset:51584
	v_add_f32_e32 v1, 1.0, v3
	v_add_f32_e32 v72, v124, v89
	v_fma_f32 v3, -v2, v2, 1.0
	v_max_f32_e32 v3, 0, v3
	ds_write2_b32 v79, v84, v2 offset1:16
	v_sqrt_f32_e32 v2, v3
	ds_read_b32 v3, v138 offset:18496
	v_rcp_f32_e32 v1, v1
	v_mul_f32_e32 v72, 0xbfb8aa3b, v72
	v_exp_f32_e32 v72, v72
	v_add_f32_e32 v76, v124, v90
	s_waitcnt lgkmcnt(0)
	v_mul_f32_e32 v1, v1, v3
	v_mul_f32_e32 v1, v2, v1
	v_add_f32_e32 v2, 1.0, v72
	v_rcp_f32_e32 v2, v2
	v_add_f32_e32 v3, v125, v73
	v_mul_f32_e32 v3, 0xbfb8aa3b, v3
	v_exp_f32_e32 v3, v3
	v_mul_f32_e32 v2, v127, v2
	v_exp_f32_e32 v72, v2
	ds_write_b32 v138, v1 offset:51264
	v_add_u32_e32 v2, 0x4800, v139
	v_add_f32_e32 v1, 1.0, v3
	ds_read2_b32 v[2:3], v2 offset0:32 offset1:64
	v_mul_f32_e32 v76, 0xbfb8aa3b, v76
	v_rcp_f32_e32 v1, v1
	v_exp_f32_e32 v76, v76
	v_fma_f32 v73, -v72, v72, 1.0
	v_max_f32_e32 v73, 0, v73
	s_waitcnt lgkmcnt(0)
	v_mul_f32_e32 v1, v1, v2
	v_add_f32_e32 v2, 1.0, v76
	v_rcp_f32_e32 v2, v2
	v_mul_f32_e32 v74, 0xbfb8aa3b, v74
	v_add_f32_e32 v77, v124, v91
	v_sqrt_f32_e32 v73, v73
	v_exp_f32_e32 v74, v74
	v_mul_f32_e32 v2, v127, v2
	v_mul_f32_e32 v77, 0xbfb8aa3b, v77
	v_exp_f32_e32 v2, v2
	v_exp_f32_e32 v77, v77
	v_mul_f32_e32 v1, v73, v1
	v_add_f32_e32 v73, 1.0, v74
	v_add_u32_e32 v76, 0x8800, v139
	v_rcp_f32_e32 v73, v73
	ds_write2_b32 v76, v72, v2 offset0:32 offset1:64
	v_add_f32_e32 v72, 1.0, v77
	v_rcp_f32_e32 v72, v72
	v_fma_f32 v74, -v2, v2, 1.0
	v_mul_f32_e32 v3, v73, v3
	v_add_f32_e32 v73, v125, v75
	v_max_f32_e32 v74, 0, v74
	v_mul_f32_e32 v73, 0xbfb8aa3b, v73
	v_mul_f32_e32 v72, v127, v72
	v_sqrt_f32_e32 v2, v74
	v_exp_f32_e32 v73, v73
	v_exp_f32_e32 v72, v72
	ds_read_b32 v74, v139 offset:18816
	v_mul_f32_e32 v2, v2, v3
	v_add_f32_e32 v3, 1.0, v73
	v_fma_f32 v73, -v72, v72, 1.0
	v_rcp_f32_e32 v3, v3
	v_max_f32_e32 v73, 0, v73
	v_sqrt_f32_e32 v73, v73
	v_add_u32_e32 v75, 0x80, v139
	ds_write2st64_b32 v75, v72, v1 offset0:137 offset1:200
	s_waitcnt lgkmcnt(1)
	v_mul_f32_e32 v1, v3, v74
	v_mul_f32_e32 v1, v73, v1
	v_add_u32_e32 v3, 0xc800, v139
	ds_write2_b32 v3, v2, v1 offset0:64 offset1:96
	v_add_u32_e32 v1, 0x8800, v140
	s_waitcnt lgkmcnt(0)
	ds_read2_b32 v[120:121], v1 offset1:32
	v_add_u32_e32 v2, 0xc800, v140
	ds_read2_b32 v[118:119], v2 offset1:32
	ds_read2_b32 v[116:117], v1 offset0:64 offset1:96
	ds_read2_b32 v[114:115], v2 offset0:64 offset1:96
	ds_read2_b32 v[112:113], v1 offset0:128 offset1:160
	ds_read2_b32 v[110:111], v2 offset0:128 offset1:160
	ds_read2_b32 v[108:109], v1 offset0:192 offset1:224
	ds_read2_b32 v[2:3], v2 offset0:192 offset1:224
	s_waitcnt lgkmcnt(5)
	v_mov_b32_e32 v74, v116
	s_waitcnt lgkmcnt(3)
	v_mov_b32_e32 v75, v113
	v_fma_f32 v1, 0, v120, v118
	v_fma_f32 v1, v1, v121, v119
	v_fma_f32 v1, v1, v116, v114
	v_fma_f32 v1, v1, v117, v115
	v_mul_f32_e32 v72, v120, v121
	s_waitcnt lgkmcnt(2)
	v_fma_f32 v73, v1, v112, v110
	v_mov_b32_e32 v76, v117
	v_mov_b32_e32 v77, v111
	v_mul_f32_e32 v1, v72, v116
	v_pk_fma_f32 v[72:73], v[72:73], v[74:75], v[76:77]
	v_mul_f32_e32 v78, v1, v117
	v_mov_b32_e32 v79, v73
	v_mov_b32_e32 v72, v112
	s_waitcnt lgkmcnt(1)
	v_mov_b32_e32 v73, v108
	v_pk_mul_f32 v[74:75], v[78:79], v[72:73]
	v_mov_b32_e32 v76, v113
	v_mov_b32_e32 v80, v113
	s_waitcnt lgkmcnt(0)
	v_mov_b32_e32 v81, v2
	v_pk_mul_f32 v[74:75], v[74:75], v[76:77]
	v_pk_fma_f32 v[72:73], v[78:79], v[72:73], v[80:81]
	v_mov_b32_e32 v76, v109
	v_mov_b32_e32 v72, v74
	v_pk_mul_f32 v[74:75], v[74:75], v[108:109]
	v_mov_b32_e32 v78, v109
	v_mov_b32_e32 v79, v3
	v_pk_mul_f32 v[74:75], v[74:75], v[76:77]
	v_pk_fma_f32 v[72:73], v[72:73], v[108:109], v[78:79]
	s_nop 0
	v_mov_b32_e32 v75, v73
	v_add_u32_e32 v72, s89, v136
	ds_write_b64 v143, v[74:75]
	s_waitcnt lgkmcnt(0)
	s_barrier
; #define LAS __attribute__((address_space(3)))
; __device__ __forceinline__ void rglru_unit(LAS unsigned char* lds, int unit, const bf16* PBp, bf16* MGp, float* SSQRp, const float* cw, const float* cbias, const float* wa, const float* ba, const float* wx, const float* bxp, const float* lam) {
;     ...
;         float h = HIN[sc];
;         { typedef float f32x2v __attribute__((ext_vector_type(2))); f32x2v pe[15];
; #pragma unroll
;           for (int s2 = 0; s2 < 15; ++s2) pe[s2] = *(const LAS f32x2v*)(PE + (s2 * 32 + sc) * 2);
; #pragma unroll
;           for (int s2 = 0; s2 < 15; ++s2) h = (s2 < ss) ? fmaf(pe[s2].x, h, pe[s2].y) : h; }
	ds_read_b32 v1, v135
	ds_read2_b64 v[96:99], v72 offset0:32 offset1:64
	ds_read2_b64 v[92:95], v72 offset0:96 offset1:128
	ds_read2_b64 v[88:91], v72 offset0:160 offset1:192
	v_add_u32_e32 v73, 0x400, v72
	v_add_u32_e32 v72, 0x800, v72
	ds_read2_b64 v[84:87], v73 offset0:96 offset1:128
	ds_read2_b64 v[80:83], v72 offset0:32 offset1:64
	ds_read2_b64 v[76:79], v72 offset0:96 offset1:128
	ds_read2_b64 v[72:75], v72 offset0:160 offset1:192
	s_and_saveexec_b64 s[2:3], s[8:9]
	s_cbranch_execz .LBB0_454
	v_add_u32_e32 v154, 0, v136
	v_add_u32_e32 v154, 0x10800, v154
	ds_read_b64 v[154:155], v154
	s_waitcnt lgkmcnt(0)
	v_fmac_f32_e32 v155, v154, v1
	v_mov_b32_e32 v1, v155
